# ssd_norm and final-norm loops unrolled x2 (both iterations' loads in flight before the first compute/stores), stacked on v82
# baseline (speedup 1.0000x reference)
; __device__ __forceinline__ void unpack8(const u32x4 v, float* f) { f[0] = bf_lo(v.x); f[1] = bf_hi(v.x); f[2] = bf_lo(v.y); f[3] = bf_hi(v.y); f[4] = bf_lo(v.z); f[5] = bf_hi(v.z); f[6] = bf_lo(v.w); f[7] = bf_hi(v.w); }
; __device__ __forceinline__ u32x4 pack8(const float* f) { u32x4 w; w.x = pk2(f[0], f[1]); w.y = pk2(f[2], f[3]); w.z = pk2(f[4], f[5]); w.w = pk2(f[6], f[7]); return w; }
; __device__ __forceinline__ void ssd_norm_phase(const Args& A) {
;     ...
;     for (int row0 = blockIdx.x * 8 + wave; row0 < NTOK; row0 += 2 * stride) {
;         u32x4 raw[2][2];
; #pragma unroll
;         for (int rr = 0; rr < 2; ++rr) { const u16* p = proj + (size_t)(row0 + rr * stride) * PLD + 3072 + 16 * lane; raw[rr][0] = *(const u32x4*)p; raw[rr][1] = *(const u32x4*)(p + 8); }
; #pragma unroll
;         for (int rr = 0; rr < 2; ++rr) { u16* p = proj + (size_t)(row0 + rr * stride) * PLD + 3072 + 16 * lane; float f[16]; unpack8(raw[rr][0], f); unpack8(raw[rr][1], f + 8);
;             float s2 = 0.f;
; #pragma unroll
;             for (int j = 0; j < 16; ++j) s2 += f[j] * f[j];
;             s2 += __shfl_xor(s2, 1); s2 += __shfl_xor(s2, 2); s2 += __shfl_xor(s2, 4); s2 += __shfl_xor(s2, 8);
;             const float rs = rsqrtf(s2 * (1.0f / 256.0f) + EPS);
; #pragma unroll
;             for (int j = 0; j < 16; ++j) f[j] = f[j] * rs * nw[j];
;             *(u32x4*)p = pack8(f); *(u32x4*)(p + 8) = pack8(f + 8); }
.LBB0_611:
	v_mad_i64_i32 v[26:27], s[0:1], v25, s12, v[18:19]
	v_add_u32_e32 v25, s11, v25
	v_lshl_add_u64 v[26:27], v[26:27], 0, v[16:17]
	v_mad_i64_i32 v[28:29], s[0:1], v25, s12, v[18:19]
	v_add_co_u32_e32 v44, vcc, 0x1000, v26
	v_lshl_add_u64 v[34:35], v[28:29], 0, v[16:17]
	s_nop 0
	v_addc_co_u32_e32 v45, vcc, 0, v27, vcc
	v_lshl_add_u64 v[42:43], v[26:27], 0, s[8:9]
	v_lshl_add_u64 v[46:47], v[34:35], 0, s[8:9]
	v_add_co_u32_e32 v48, vcc, s13, v34
	global_load_dwordx4 v[26:29], v[42:43], off offset:16
	global_load_dwordx4 v[30:33], v[44:45], off offset:2048
	v_addc_co_u32_e32 v49, vcc, 0, v35, vcc
	global_load_dwordx4 v[34:37], v[46:47], off offset:16
	global_load_dwordx4 v[38:41], v[48:49], off offset:2048
	v_add_u32_e32 v25, s11, v25
	v_cmp_lt_i32_e64 s[0:1], s15, v25
	s_or_b64 s[6:7], s[0:1], s[6:7]
	v_mad_i64_i32 v[154:155], s[0:1], v25, s12, v[18:19]
	v_add_u32_e32 v25, s11, v25
	v_lshl_add_u64 v[154:155], v[154:155], 0, v[16:17]
	v_mad_i64_i32 v[156:157], s[0:1], v25, s12, v[18:19]
	v_add_co_u32_e32 v172, vcc, 0x1000, v154
	v_lshl_add_u64 v[162:163], v[156:157], 0, v[16:17]
	s_nop 0
	v_addc_co_u32_e32 v173, vcc, 0, v155, vcc
	v_lshl_add_u64 v[170:171], v[154:155], 0, s[8:9]
	v_lshl_add_u64 v[174:175], v[162:163], 0, s[8:9]
	v_add_co_u32_e32 v176, vcc, s13, v162
	global_load_dwordx4 v[154:157], v[170:171], off offset:16
	global_load_dwordx4 v[158:161], v[172:173], off offset:2048
	v_addc_co_u32_e32 v177, vcc, 0, v163, vcc
	global_load_dwordx4 v[162:165], v[174:175], off offset:16
	global_load_dwordx4 v[166:169], v[176:177], off offset:2048
	v_add_u32_e32 v25, s11, v25
	v_cmp_lt_i32_e64 s[0:1], s15, v25
	s_or_b64 s[6:7], s[0:1], s[6:7]
	s_waitcnt vmcnt(7)
	v_lshlrev_b32_e32 v50, 16, v29
	s_waitcnt vmcnt(6)
	v_and_b32_e32 v59, 0xffff0000, v30
	v_lshlrev_b32_e32 v58, 16, v30
	v_mov_b32_e32 v91, v59
	s_waitcnt vmcnt(4)
	v_and_b32_e32 v73, 0xffff0000, v38
	v_lshlrev_b32_e32 v72, 16, v38
	v_mov_b32_e32 v90, v73
	v_lshlrev_b32_e32 v56, 16, v32
	v_and_b32_e32 v57, 0xffff0000, v32
	v_lshlrev_b32_e32 v32, 16, v31
	v_lshlrev_b32_e32 v70, 16, v40
	v_and_b32_e32 v71, 0xffff0000, v40
	v_lshlrev_b32_e32 v40, 16, v39
	v_mov_b32_e32 v89, v58
	v_mov_b32_e32 v88, v72
	v_pk_mul_f32 v[90:91], v[90:91], v[90:91]
	v_and_b32_e32 v51, 0xffff0000, v29
	v_lshlrev_b32_e32 v52, 16, v28
	v_and_b32_e32 v53, 0xffff0000, v28
	v_lshlrev_b32_e32 v28, 16, v27
	v_and_b32_e32 v29, 0xffff0000, v27
	v_lshlrev_b32_e32 v54, 16, v26
	v_and_b32_e32 v55, 0xffff0000, v26
	v_lshlrev_b32_e32 v26, 16, v33
	v_and_b32_e32 v27, 0xffff0000, v33
	v_and_b32_e32 v33, 0xffff0000, v31
	v_lshlrev_b32_e32 v64, 16, v37
	v_and_b32_e32 v65, 0xffff0000, v37
	v_lshlrev_b32_e32 v66, 16, v36
	v_and_b32_e32 v67, 0xffff0000, v36
	v_lshlrev_b32_e32 v36, 16, v35
	v_and_b32_e32 v37, 0xffff0000, v35
	v_lshlrev_b32_e32 v68, 16, v34
	v_and_b32_e32 v69, 0xffff0000, v34
	v_lshlrev_b32_e32 v34, 16, v41
	v_and_b32_e32 v35, 0xffff0000, v41
	v_and_b32_e32 v41, 0xffff0000, v39
	v_mov_b32_e32 v85, v32
	v_mov_b32_e32 v84, v40
	v_pk_fma_f32 v[88:89], v[88:89], v[88:89], v[90:91]
	v_mov_b32_e32 v87, v33
	v_mov_b32_e32 v86, v41
	v_pk_fma_f32 v[84:85], v[84:85], v[84:85], v[88:89]
	v_mov_b32_e32 v81, v56
	v_mov_b32_e32 v80, v70
	v_pk_fma_f32 v[84:85], v[86:87], v[86:87], v[84:85]
	v_mov_b32_e32 v83, v57
	v_mov_b32_e32 v82, v71
	v_pk_fma_f32 v[80:81], v[80:81], v[80:81], v[84:85]
	v_mov_b32_e32 v77, v26
	v_mov_b32_e32 v76, v34
	v_pk_fma_f32 v[80:81], v[82:83], v[82:83], v[80:81]
	v_mov_b32_e32 v79, v27
	v_mov_b32_e32 v78, v35
	v_pk_fma_f32 v[76:77], v[76:77], v[76:77], v[80:81]
	v_mov_b32_e32 v39, v54
	v_mov_b32_e32 v38, v68
	v_pk_fma_f32 v[76:77], v[78:79], v[78:79], v[76:77]
	v_pk_mul_f32 v[62:63], v[28:29], v[28:29]
	v_mov_b32_e32 v75, v55
	v_pk_mul_f32 v[96:97], v[36:37], v[36:37]
	v_mov_b32_e32 v74, v69
	v_pk_fma_f32 v[38:39], v[38:39], v[38:39], v[76:77]
	v_mov_b32_e32 v99, v62
	v_mov_b32_e32 v98, v96
	v_pk_fma_f32 v[38:39], v[74:75], v[74:75], v[38:39]
	v_pk_mul_f32 v[60:61], v[52:53], v[52:53]
	v_pk_mul_f32 v[94:95], v[66:67], v[66:67]
	v_mov_b32_e32 v62, v97
	v_pk_add_f32 v[38:39], v[98:99], v[38:39]
	v_mov_b32_e32 v101, v60
	v_mov_b32_e32 v100, v94
	v_pk_add_f32 v[38:39], v[62:63], v[38:39]
	v_pk_mul_f32 v[30:31], v[50:51], v[50:51]
	v_pk_mul_f32 v[92:93], v[64:65], v[64:65]
	v_mov_b32_e32 v60, v95
	v_pk_add_f32 v[38:39], v[100:101], v[38:39]
	v_mov_b32_e32 v103, v30
	v_mov_b32_e32 v102, v92
	v_pk_add_f32 v[38:39], v[60:61], v[38:39]
	v_mov_b32_e32 v30, v93
	v_pk_add_f32 v[38:39], v[102:103], v[38:39]
	s_nop 0
	v_pk_add_f32 v[30:31], v[30:31], v[38:39]
	ds_bpermute_b32 v39, v21, v31
	ds_bpermute_b32 v38, v21, v30
	s_waitcnt lgkmcnt(0)
	v_pk_add_f32 v[30:31], v[30:31], v[38:39]
	ds_bpermute_b32 v39, v22, v31
	ds_bpermute_b32 v38, v22, v30
	s_waitcnt lgkmcnt(0)
	v_pk_add_f32 v[30:31], v[30:31], v[38:39]
	ds_bpermute_b32 v39, v23, v31
	ds_bpermute_b32 v38, v23, v30
	s_waitcnt lgkmcnt(0)
	v_pk_add_f32 v[30:31], v[30:31], v[38:39]
	ds_bpermute_b32 v39, v24, v31
	ds_bpermute_b32 v38, v24, v30
	s_waitcnt lgkmcnt(0)
; __device__ __forceinline__ void unpack8(const u32x4 v, float* f) { f[0] = bf_lo(v.x); f[1] = bf_hi(v.x); f[2] = bf_lo(v.y); f[3] = bf_hi(v.y); f[4] = bf_lo(v.z); f[5] = bf_hi(v.z); f[6] = bf_lo(v.w); f[7] = bf_hi(v.w); }
; __device__ __forceinline__ u32x4 pack8(const float* f) { u32x4 w; w.x = pk2(f[0], f[1]); w.y = pk2(f[2], f[3]); w.z = pk2(f[4], f[5]); w.w = pk2(f[6], f[7]); return w; }
; __device__ __forceinline__ void ssd_norm_phase(const Args& A) {
;     ...
;         for (int rr = 0; rr < 2; ++rr) { u16* p = proj + (size_t)(row0 + rr * stride) * PLD + 3072 + 16 * lane; float f[16]; unpack8(raw[rr][0], f); unpack8(raw[rr][1], f + 8);
;             float s2 = 0.f;
; #pragma unroll
;             for (int j = 0; j < 16; ++j) s2 += f[j] * f[j];
;             s2 += __shfl_xor(s2, 1); s2 += __shfl_xor(s2, 2); s2 += __shfl_xor(s2, 4); s2 += __shfl_xor(s2, 8);
;             const float rs = rsqrtf(s2 * (1.0f / 256.0f) + EPS);
; #pragma unroll
;             for (int j = 0; j < 16; ++j) f[j] = f[j] * rs * nw[j];
;             *(u32x4*)p = pack8(f); *(u32x4*)(p + 8) = pack8(f + 8); }
	v_pk_add_f32 v[30:31], v[30:31], v[38:39]
	s_nop 0
	v_pk_fma_f32 v[30:31], v[30:31], s[10:11], v[20:21] op_sel_hi:[1,0,0]
	s_nop 0
	v_mul_f32_e32 v38, 0x4b800000, v31
	v_cmp_gt_f32_e64 s[0:1], s14, v31
	v_mul_f32_e32 v39, 0x4b800000, v30
	v_cmp_gt_f32_e32 vcc, s14, v30
	v_cndmask_b32_e64 v31, v31, v38, s[0:1]
	v_rsq_f32_e32 v31, v31
	v_cndmask_b32_e32 v30, v30, v39, vcc
	v_rsq_f32_e32 v38, v30
	v_mul_f32_e32 v30, 0x45800000, v31
	v_cndmask_b32_e64 v30, v31, v30, s[0:1]
	v_mul_f32_e32 v39, 0x45800000, v38
	v_cndmask_b32_e32 v38, v38, v39, vcc
	v_pk_mul_f32 v[58:59], v[30:31], v[58:59] op_sel_hi:[0,1]
	v_pk_mul_f32 v[32:33], v[30:31], v[32:33] op_sel_hi:[0,1]
	v_pk_mul_f32 v[56:57], v[30:31], v[56:57] op_sel_hi:[0,1]
	v_pk_mul_f32 v[26:27], v[30:31], v[26:27] op_sel_hi:[0,1]
	v_pk_mul_f32 v[54:55], v[30:31], v[54:55] op_sel_hi:[0,1]
	v_pk_mul_f32 v[28:29], v[30:31], v[28:29] op_sel_hi:[0,1]
	v_pk_mul_f32 v[52:53], v[30:31], v[52:53] op_sel_hi:[0,1]
	v_pk_mul_f32 v[30:31], v[30:31], v[50:51] op_sel_hi:[0,1]
	v_pk_mul_f32 v[50:51], v[38:39], v[72:73] op_sel_hi:[0,1]
	v_pk_mul_f32 v[40:41], v[38:39], v[40:41] op_sel_hi:[0,1]
	v_pk_mul_f32 v[60:61], v[38:39], v[70:71] op_sel_hi:[0,1]
	v_pk_mul_f32 v[34:35], v[38:39], v[34:35] op_sel_hi:[0,1]
	v_pk_mul_f32 v[62:63], v[38:39], v[68:69] op_sel_hi:[0,1]
	v_pk_mul_f32 v[36:37], v[38:39], v[36:37] op_sel_hi:[0,1]
	v_pk_mul_f32 v[66:67], v[38:39], v[66:67] op_sel_hi:[0,1]
	v_pk_mul_f32 v[38:39], v[38:39], v[64:65] op_sel_hi:[0,1]
	v_pk_mul_f32 v[58:59], v[12:13], v[58:59]
	v_pk_mul_f32 v[32:33], v[14:15], v[32:33]
	v_pk_mul_f32 v[56:57], v[8:9], v[56:57]
	v_pk_mul_f32 v[64:65], v[10:11], v[26:27]
	v_pk_mul_f32 v[54:55], v[4:5], v[54:55]
	v_pk_mul_f32 v[68:69], v[6:7], v[28:29]
	v_pk_mul_f32 v[52:53], v[0:1], v[52:53]
	v_pk_mul_f32 v[70:71], v[2:3], v[30:31]
	v_pk_mul_f32 v[50:51], v[12:13], v[50:51]
	v_pk_mul_f32 v[40:41], v[14:15], v[40:41]
	v_pk_mul_f32 v[60:61], v[8:9], v[60:61]
	v_pk_mul_f32 v[72:73], v[10:11], v[34:35]
	v_pk_mul_f32 v[62:63], v[4:5], v[62:63]
	v_pk_mul_f32 v[74:75], v[6:7], v[36:37]
	v_pk_mul_f32 v[66:67], v[0:1], v[66:67]
	v_pk_mul_f32 v[76:77], v[2:3], v[38:39]
	v_cvt_pk_bf16_f32 v26, v58, v59
	v_cvt_pk_bf16_f32 v27, v32, v33
	v_cvt_pk_bf16_f32 v28, v56, v57
	v_cvt_pk_bf16_f32 v29, v64, v65
	v_cvt_pk_bf16_f32 v30, v54, v55
	v_cvt_pk_bf16_f32 v31, v68, v69
	v_cvt_pk_bf16_f32 v32, v52, v53
	v_cvt_pk_bf16_f32 v33, v70, v71
	v_cvt_pk_bf16_f32 v34, v50, v51
	v_cvt_pk_bf16_f32 v35, v40, v41
	v_cvt_pk_bf16_f32 v36, v60, v61
	v_cvt_pk_bf16_f32 v37, v72, v73
	v_cvt_pk_bf16_f32 v38, v62, v63
	v_cvt_pk_bf16_f32 v39, v74, v75
	v_cvt_pk_bf16_f32 v40, v66, v67
	v_cvt_pk_bf16_f32 v41, v76, v77
	global_store_dwordx4 v[44:45], v[26:29], off offset:2048
	global_store_dwordx4 v[42:43], v[30:33], off offset:16
	global_store_dwordx4 v[48:49], v[34:37], off offset:2048
	global_store_dwordx4 v[46:47], v[38:41], off offset:16
	s_waitcnt vmcnt(7)
	v_lshlrev_b32_e32 v178, 16, v157
	s_waitcnt vmcnt(6)
	v_and_b32_e32 v187, 0xffff0000, v158
	v_lshlrev_b32_e32 v186, 16, v158
	v_mov_b32_e32 v219, v187
	s_waitcnt vmcnt(4)
	v_and_b32_e32 v201, 0xffff0000, v166
	v_lshlrev_b32_e32 v200, 16, v166
	v_mov_b32_e32 v218, v201
	v_lshlrev_b32_e32 v184, 16, v160
	v_and_b32_e32 v185, 0xffff0000, v160
	v_lshlrev_b32_e32 v160, 16, v159
	v_lshlrev_b32_e32 v198, 16, v168
	v_and_b32_e32 v199, 0xffff0000, v168
	v_lshlrev_b32_e32 v168, 16, v167
	v_mov_b32_e32 v217, v186
	v_mov_b32_e32 v216, v200
	v_pk_mul_f32 v[218:219], v[218:219], v[218:219]
	v_and_b32_e32 v179, 0xffff0000, v157
	v_lshlrev_b32_e32 v180, 16, v156
	v_and_b32_e32 v181, 0xffff0000, v156
	v_lshlrev_b32_e32 v156, 16, v155
	v_and_b32_e32 v157, 0xffff0000, v155
	v_lshlrev_b32_e32 v182, 16, v154
	v_and_b32_e32 v183, 0xffff0000, v154
	v_lshlrev_b32_e32 v154, 16, v161
	v_and_b32_e32 v155, 0xffff0000, v161
	v_and_b32_e32 v161, 0xffff0000, v159
	v_lshlrev_b32_e32 v192, 16, v165
	v_and_b32_e32 v193, 0xffff0000, v165
	v_lshlrev_b32_e32 v194, 16, v164
	v_and_b32_e32 v195, 0xffff0000, v164
	v_lshlrev_b32_e32 v164, 16, v163
	v_and_b32_e32 v165, 0xffff0000, v163
	v_lshlrev_b32_e32 v196, 16, v162
	v_and_b32_e32 v197, 0xffff0000, v162
	v_lshlrev_b32_e32 v162, 16, v169
	v_and_b32_e32 v163, 0xffff0000, v169
	v_and_b32_e32 v169, 0xffff0000, v167
	v_mov_b32_e32 v213, v160
	v_mov_b32_e32 v212, v168
	v_pk_fma_f32 v[216:217], v[216:217], v[216:217], v[218:219]
	v_mov_b32_e32 v215, v161
	v_mov_b32_e32 v214, v169
	v_pk_fma_f32 v[212:213], v[212:213], v[212:213], v[216:217]
	v_mov_b32_e32 v209, v184
	v_mov_b32_e32 v208, v198
	v_pk_fma_f32 v[212:213], v[214:215], v[214:215], v[212:213]
	v_mov_b32_e32 v211, v185
	v_mov_b32_e32 v210, v199
	v_pk_fma_f32 v[208:209], v[208:209], v[208:209], v[212:213]
	v_mov_b32_e32 v205, v154
	v_mov_b32_e32 v204, v162
	v_pk_fma_f32 v[208:209], v[210:211], v[210:211], v[208:209]
	v_mov_b32_e32 v207, v155
	v_mov_b32_e32 v206, v163
	v_pk_fma_f32 v[204:205], v[204:205], v[204:205], v[208:209]
	v_mov_b32_e32 v167, v182
	v_mov_b32_e32 v166, v196
	v_pk_fma_f32 v[204:205], v[206:207], v[206:207], v[204:205]
	v_pk_mul_f32 v[190:191], v[156:157], v[156:157]
	v_mov_b32_e32 v203, v183
	v_pk_mul_f32 v[224:225], v[164:165], v[164:165]
	v_mov_b32_e32 v202, v197
	v_pk_fma_f32 v[166:167], v[166:167], v[166:167], v[204:205]
	v_mov_b32_e32 v227, v190
	v_mov_b32_e32 v226, v224
	v_pk_fma_f32 v[166:167], v[202:203], v[202:203], v[166:167]
	v_pk_mul_f32 v[188:189], v[180:181], v[180:181]
	v_pk_mul_f32 v[222:223], v[194:195], v[194:195]
	v_mov_b32_e32 v190, v225
	v_pk_add_f32 v[166:167], v[226:227], v[166:167]
	v_mov_b32_e32 v229, v188
	v_mov_b32_e32 v228, v222
	v_pk_add_f32 v[166:167], v[190:191], v[166:167]
	v_pk_mul_f32 v[158:159], v[178:179], v[178:179]
	v_pk_mul_f32 v[220:221], v[192:193], v[192:193]
	v_mov_b32_e32 v188, v223
	v_pk_add_f32 v[166:167], v[228:229], v[166:167]
	v_mov_b32_e32 v231, v158
	v_mov_b32_e32 v230, v220
	v_pk_add_f32 v[166:167], v[188:189], v[166:167]
	v_mov_b32_e32 v158, v221
	v_pk_add_f32 v[166:167], v[230:231], v[166:167]
	s_nop 0
	v_pk_add_f32 v[158:159], v[158:159], v[166:167]
	ds_bpermute_b32 v167, v21, v159
	ds_bpermute_b32 v166, v21, v158
	s_waitcnt lgkmcnt(0)
; __device__ __forceinline__ u32x4 pack8(const float* f) { u32x4 w; w.x = pk2(f[0], f[1]); w.y = pk2(f[2], f[3]); w.z = pk2(f[4], f[5]); w.w = pk2(f[6], f[7]); return w; }
; __device__ __forceinline__ void ssd_norm_phase(const Args& A) {
;     ...
;             s2 += __shfl_xor(s2, 1); s2 += __shfl_xor(s2, 2); s2 += __shfl_xor(s2, 4); s2 += __shfl_xor(s2, 8);
;             const float rs = rsqrtf(s2 * (1.0f / 256.0f) + EPS);
; #pragma unroll
;             for (int j = 0; j < 16; ++j) f[j] = f[j] * rs * nw[j];
;             *(u32x4*)p = pack8(f); *(u32x4*)(p + 8) = pack8(f + 8); }
	v_pk_add_f32 v[158:159], v[158:159], v[166:167]
	ds_bpermute_b32 v167, v22, v159
	ds_bpermute_b32 v166, v22, v158
	s_waitcnt lgkmcnt(0)
	v_pk_add_f32 v[158:159], v[158:159], v[166:167]
	ds_bpermute_b32 v167, v23, v159
	ds_bpermute_b32 v166, v23, v158
	s_waitcnt lgkmcnt(0)
	v_pk_add_f32 v[158:159], v[158:159], v[166:167]
	ds_bpermute_b32 v167, v24, v159
	ds_bpermute_b32 v166, v24, v158
	s_waitcnt lgkmcnt(0)
	v_pk_add_f32 v[158:159], v[158:159], v[166:167]
	s_nop 0
	v_pk_fma_f32 v[158:159], v[158:159], s[10:11], v[20:21] op_sel_hi:[1,0,0]
	s_nop 0
	v_mul_f32_e32 v166, 0x4b800000, v159
	v_cmp_gt_f32_e64 s[0:1], s14, v159
	v_mul_f32_e32 v167, 0x4b800000, v158
	v_cmp_gt_f32_e32 vcc, s14, v158
	v_cndmask_b32_e64 v159, v159, v166, s[0:1]
	v_rsq_f32_e32 v159, v159
	v_cndmask_b32_e32 v158, v158, v167, vcc
	v_rsq_f32_e32 v166, v158
	v_mul_f32_e32 v158, 0x45800000, v159
	v_cndmask_b32_e64 v158, v159, v158, s[0:1]
	v_mul_f32_e32 v167, 0x45800000, v166
	v_cndmask_b32_e32 v166, v166, v167, vcc
	v_pk_mul_f32 v[186:187], v[158:159], v[186:187] op_sel_hi:[0,1]
	v_pk_mul_f32 v[160:161], v[158:159], v[160:161] op_sel_hi:[0,1]
	v_pk_mul_f32 v[184:185], v[158:159], v[184:185] op_sel_hi:[0,1]
	v_pk_mul_f32 v[154:155], v[158:159], v[154:155] op_sel_hi:[0,1]
	v_pk_mul_f32 v[182:183], v[158:159], v[182:183] op_sel_hi:[0,1]
	v_pk_mul_f32 v[156:157], v[158:159], v[156:157] op_sel_hi:[0,1]
	v_pk_mul_f32 v[180:181], v[158:159], v[180:181] op_sel_hi:[0,1]
	v_pk_mul_f32 v[158:159], v[158:159], v[178:179] op_sel_hi:[0,1]
	v_pk_mul_f32 v[178:179], v[166:167], v[200:201] op_sel_hi:[0,1]
	v_pk_mul_f32 v[168:169], v[166:167], v[168:169] op_sel_hi:[0,1]
	v_pk_mul_f32 v[188:189], v[166:167], v[198:199] op_sel_hi:[0,1]
	v_pk_mul_f32 v[162:163], v[166:167], v[162:163] op_sel_hi:[0,1]
	v_pk_mul_f32 v[190:191], v[166:167], v[196:197] op_sel_hi:[0,1]
	v_pk_mul_f32 v[164:165], v[166:167], v[164:165] op_sel_hi:[0,1]
	v_pk_mul_f32 v[194:195], v[166:167], v[194:195] op_sel_hi:[0,1]
	v_pk_mul_f32 v[166:167], v[166:167], v[192:193] op_sel_hi:[0,1]
	v_pk_mul_f32 v[186:187], v[12:13], v[186:187]
	v_pk_mul_f32 v[160:161], v[14:15], v[160:161]
	v_pk_mul_f32 v[184:185], v[8:9], v[184:185]
	v_pk_mul_f32 v[192:193], v[10:11], v[154:155]
	v_pk_mul_f32 v[182:183], v[4:5], v[182:183]
	v_pk_mul_f32 v[196:197], v[6:7], v[156:157]
	v_pk_mul_f32 v[180:181], v[0:1], v[180:181]
	v_pk_mul_f32 v[198:199], v[2:3], v[158:159]
	v_pk_mul_f32 v[178:179], v[12:13], v[178:179]
	v_pk_mul_f32 v[168:169], v[14:15], v[168:169]
	v_pk_mul_f32 v[188:189], v[8:9], v[188:189]
	v_pk_mul_f32 v[200:201], v[10:11], v[162:163]
	v_pk_mul_f32 v[190:191], v[4:5], v[190:191]
	v_pk_mul_f32 v[202:203], v[6:7], v[164:165]
	v_pk_mul_f32 v[194:195], v[0:1], v[194:195]
	v_pk_mul_f32 v[204:205], v[2:3], v[166:167]
	v_cvt_pk_bf16_f32 v154, v186, v187
	v_cvt_pk_bf16_f32 v155, v160, v161
	v_cvt_pk_bf16_f32 v156, v184, v185
	v_cvt_pk_bf16_f32 v157, v192, v193
	v_cvt_pk_bf16_f32 v158, v182, v183
	v_cvt_pk_bf16_f32 v159, v196, v197
	v_cvt_pk_bf16_f32 v160, v180, v181
	v_cvt_pk_bf16_f32 v161, v198, v199
	v_cvt_pk_bf16_f32 v162, v178, v179
	v_cvt_pk_bf16_f32 v163, v168, v169
	v_cvt_pk_bf16_f32 v164, v188, v189
	v_cvt_pk_bf16_f32 v165, v200, v201
	v_cvt_pk_bf16_f32 v166, v190, v191
	v_cvt_pk_bf16_f32 v167, v202, v203
	v_cvt_pk_bf16_f32 v168, v194, v195
	v_cvt_pk_bf16_f32 v169, v204, v205
	global_store_dwordx4 v[172:173], v[154:157], off offset:2048
	global_store_dwordx4 v[170:171], v[158:161], off offset:16
	global_store_dwordx4 v[176:177], v[162:165], off offset:2048
	global_store_dwordx4 v[174:175], v[166:169], off offset:16
	s_andn2_b64 exec, exec, s[6:7]
	s_cbranch_execnz .LBB0_611

; __device__ __forceinline__ void unpack8(const u32x4 v, float* f) { f[0] = bf_lo(v.x); f[1] = bf_hi(v.x); f[2] = bf_lo(v.y); f[3] = bf_hi(v.y); f[4] = bf_lo(v.z); f[5] = bf_hi(v.z); f[6] = bf_lo(v.w); f[7] = bf_hi(v.w); }
; __device__ __forceinline__ void final_norm_phase(const Args& A) {
;     ...
;     for (int row = blockIdx.x * 4 + (threadIdx.x >> 7); row < NTOK; row += gridDim.x * 8) {
;         const u32x4 r0 = *(const u32x4*)(xb + (size_t)row * DM + c8); const int row2 = (row + (int)gridDim.x * 4 < NTOK) ? row + (int)gridDim.x * 4 : row; const u32x4 r1 = *(const u32x4*)(xb + (size_t)row2 * DM + c8);
;         float s0, s1;
;         { const f32x4 p0 = *(const f32x4*)(ss4 + (size_t)row * 16), p1 = *(const f32x4*)(ss4 + (size_t)row * 16 + 4), p2 = *(const f32x4*)(ss4 + (size_t)row * 16 + 8), p3 = *(const f32x4*)(ss4 + (size_t)row * 16 + 12);
;             s0 = ((((p0[0] + p0[1]) + (p0[2] + p0[3])) + ((p1[0] + p1[1]) + (p1[2] + p1[3]))) + (((p2[0] + p2[1]) + (p2[2] + p2[3])) + ((p3[0] + p3[1]) + (p3[2] + p3[3])))); }
;         { const f32x4 p0 = *(const f32x4*)(ss4 + (size_t)row2 * 16), p1 = *(const f32x4*)(ss4 + (size_t)row2 * 16 + 4), p2 = *(const f32x4*)(ss4 + (size_t)row2 * 16 + 8), p3 = *(const f32x4*)(ss4 + (size_t)row2 * 16 + 12);
;             s1 = ((((p0[0] + p0[1]) + (p0[2] + p0[3])) + ((p1[0] + p1[1]) + (p1[2] + p1[3]))) + (((p2[0] + p2[1]) + (p2[2] + p2[3])) + ((p3[0] + p3[1]) + (p3[2] + p3[3])))); }
;         float f[8]; unpack8(r0, f); float rs = rsqrtf(s0 * (1.0f / 1024.0f) + EPS);
;         *(f32x4*)(out + (size_t)row * DM + c8) = (f32x4){f[0], f[1], f[2], f[3]} * rs * g0; *(f32x4*)(out + (size_t)row * DM + c8 + 4) = (f32x4){f[4], f[5], f[6], f[7]} * rs * g1;
;         unpack8(r1, f); rs = rsqrtf(s1 * (1.0f / 1024.0f) + EPS);
;         *(f32x4*)(out + (size_t)row2 * DM + c8) = (f32x4){f[0], f[1], f[2], f[3]} * rs * g0; *(f32x4*)(out + (size_t)row2 * DM + c8 + 4) = (f32x4){f[4], f[5], f[6], f[7]} * rs * g1;
.LBB0_1351:
	v_lshl_add_u32 v78, s8, 1, v14
	v_add_u32_e32 v13, s8, v14
	v_ashrrev_i32_e32 v15, 31, v14
	v_cmp_gt_i32_e32 vcc, s7, v13
	v_lshlrev_b64 v[16:17], 6, v[14:15]
	v_lshl_add_u64 v[32:33], s[2:3], 0, v[16:17]
	v_cndmask_b32_e32 v56, v14, v13, vcc
	v_ashrrev_i32_e32 v57, 31, v56
	global_load_dwordx4 v[16:19], v[32:33], off
	global_load_dwordx4 v[20:23], v[32:33], off offset:32
	global_load_dwordx4 v[24:27], v[32:33], off offset:16
	global_load_dwordx4 v[28:31], v[32:33], off offset:48
	v_lshlrev_b64 v[32:33], 11, v[14:15]
	v_lshlrev_b64 v[36:37], 6, v[56:57]
	v_lshl_add_u64 v[32:33], v[8:9], 0, v[32:33]
	v_lshl_add_u64 v[52:53], s[2:3], 0, v[36:37]
	global_load_dwordx4 v[32:35], v[32:33], off
	s_nop 0
	global_load_dwordx4 v[36:39], v[52:53], off
	global_load_dwordx4 v[40:43], v[52:53], off offset:32
	global_load_dwordx4 v[44:47], v[52:53], off offset:16
	global_load_dwordx4 v[48:51], v[52:53], off offset:48
	v_lshlrev_b64 v[52:53], 11, v[56:57]
	v_lshl_add_u64 v[52:53], v[8:9], 0, v[52:53]
	global_load_dwordx4 v[52:55], v[52:53], off
	v_lshlrev_b64 v[14:15], 12, v[14:15]
	v_lshl_add_u64 v[58:59], v[10:11], 0, v[14:15]
	v_add_u32_e32 v77, s8, v78
	v_ashrrev_i32_e32 v79, 31, v78
	v_cmp_gt_i32_e32 vcc, s7, v77
	v_lshlrev_b64 v[80:81], 6, v[78:79]
	v_lshl_add_u64 v[96:97], s[2:3], 0, v[80:81]
	v_cndmask_b32_e32 v120, v78, v77, vcc
	v_ashrrev_i32_e32 v121, 31, v120
	global_load_dwordx4 v[80:83], v[96:97], off
	global_load_dwordx4 v[84:87], v[96:97], off offset:32
	global_load_dwordx4 v[88:91], v[96:97], off offset:16
	global_load_dwordx4 v[92:95], v[96:97], off offset:48
	v_lshlrev_b64 v[96:97], 11, v[78:79]
	v_lshlrev_b64 v[100:101], 6, v[120:121]
	v_lshl_add_u64 v[96:97], v[8:9], 0, v[96:97]
	v_lshl_add_u64 v[116:117], s[2:3], 0, v[100:101]
	global_load_dwordx4 v[96:99], v[96:97], off
	s_nop 0
	global_load_dwordx4 v[100:103], v[116:117], off
	global_load_dwordx4 v[104:107], v[116:117], off offset:32
	global_load_dwordx4 v[108:111], v[116:117], off offset:16
	global_load_dwordx4 v[112:115], v[116:117], off offset:48
	v_lshlrev_b64 v[116:117], 11, v[120:121]
	v_lshl_add_u64 v[116:117], v[8:9], 0, v[116:117]
	global_load_dwordx4 v[116:119], v[116:117], off
	v_lshlrev_b64 v[78:79], 12, v[78:79]
	v_lshl_add_u64 v[122:123], v[10:11], 0, v[78:79]
	s_waitcnt vmcnt(19)
	v_mov_b32_e32 v14, v16
	s_waitcnt vmcnt(18)
	v_mov_b32_e32 v15, v20
	v_mov_b32_e32 v20, v17
	v_mov_b32_e32 v16, v18
	v_mov_b32_e32 v17, v22
	v_mov_b32_e32 v22, v19
	s_waitcnt vmcnt(17)
	v_mov_b32_e32 v18, v24
	s_waitcnt vmcnt(16)
	v_mov_b32_e32 v19, v28
	v_mov_b32_e32 v28, v25
	v_mov_b32_e32 v24, v26
	v_mov_b32_e32 v25, v30
	v_mov_b32_e32 v30, v27
	v_pk_add_f32 v[14:15], v[14:15], v[20:21]
	v_pk_add_f32 v[16:17], v[16:17], v[22:23]
	v_pk_add_f32 v[18:19], v[18:19], v[28:29]
	v_pk_add_f32 v[20:21], v[24:25], v[30:31]
	v_pk_add_f32 v[14:15], v[14:15], v[16:17]
	v_pk_add_f32 v[16:17], v[18:19], v[20:21]
	s_waitcnt vmcnt(14)
	v_mov_b32_e32 v18, v36
	s_waitcnt vmcnt(13)
	v_mov_b32_e32 v19, v40
	v_mov_b32_e32 v40, v37
	v_mov_b32_e32 v20, v38
	v_mov_b32_e32 v21, v42
	v_mov_b32_e32 v42, v39
	s_waitcnt vmcnt(12)
	v_mov_b32_e32 v22, v44
	s_waitcnt vmcnt(11)
	v_mov_b32_e32 v23, v48
	v_mov_b32_e32 v48, v45
	v_mov_b32_e32 v24, v46
	v_mov_b32_e32 v25, v50
	v_mov_b32_e32 v50, v47
	v_pk_add_f32 v[14:15], v[14:15], v[16:17]
	v_pk_add_f32 v[16:17], v[18:19], v[40:41]
	v_pk_add_f32 v[18:19], v[20:21], v[42:43]
	v_pk_add_f32 v[20:21], v[22:23], v[48:49]
	v_pk_add_f32 v[22:23], v[24:25], v[50:51]
	v_pk_add_f32 v[16:17], v[16:17], v[18:19]
	v_pk_add_f32 v[18:19], v[20:21], v[22:23]
	v_mov_b32_e32 v21, v14
	v_pk_add_f32 v[16:17], v[16:17], v[18:19]
	v_lshlrev_b32_e32 v26, 16, v32
	v_mov_b32_e32 v20, v16
	v_mov_b32_e32 v14, v17
	v_pk_add_f32 v[14:15], v[20:21], v[14:15]
	v_and_b32_e32 v27, 0xffff0000, v32
	v_pk_fma_f32 v[14:15], v[14:15], s[6:7], v[12:13] op_sel_hi:[1,0,0]
	v_lshlrev_b32_e32 v32, 16, v33
	v_mul_f32_e32 v16, 0x4b800000, v15
	v_cmp_gt_f32_e32 vcc, s9, v15
	v_mul_f32_e32 v17, 0x4b800000, v14
	v_cmp_gt_f32_e64 s[0:1], s9, v14
	v_cndmask_b32_e32 v15, v15, v16, vcc
	v_rsq_f32_e32 v15, v15
	v_cndmask_b32_e64 v14, v14, v17, s[0:1]
	v_rsq_f32_e32 v24, v14
	v_and_b32_e32 v33, 0xffff0000, v33
	v_mul_f32_e32 v14, 0x45800000, v15
	v_cndmask_b32_e32 v14, v15, v14, vcc
	v_lshlrev_b32_e32 v60, 16, v34
	v_and_b32_e32 v61, 0xffff0000, v34
	v_lshlrev_b32_e32 v34, 16, v35
	v_and_b32_e32 v35, 0xffff0000, v35
	v_pk_mul_f32 v[18:19], v[14:15], v[26:27] op_sel_hi:[0,1]
	v_pk_mul_f32 v[16:17], v[14:15], v[32:33] op_sel_hi:[0,1]
	v_pk_mul_f32 v[22:23], v[14:15], v[60:61] op_sel_hi:[0,1]
	v_pk_mul_f32 v[20:21], v[14:15], v[34:35] op_sel_hi:[0,1]
	v_pk_mul_f32 v[16:17], v[6:7], v[16:17]
	v_pk_mul_f32 v[14:15], v[4:5], v[18:19]
	v_pk_mul_f32 v[20:21], v[2:3], v[20:21]
	v_pk_mul_f32 v[18:19], v[0:1], v[22:23]
	global_store_dwordx4 v[58:59], v[14:17], off
	global_store_dwordx4 v[58:59], v[18:21], off offset:16
	s_waitcnt vmcnt(12)
; __device__ __forceinline__ void unpack8(const u32x4 v, float* f) { f[0] = bf_lo(v.x); f[1] = bf_hi(v.x); f[2] = bf_lo(v.y); f[3] = bf_hi(v.y); f[4] = bf_lo(v.z); f[5] = bf_hi(v.z); f[6] = bf_lo(v.w); f[7] = bf_hi(v.w); }
; __device__ __forceinline__ void final_norm_phase(const Args& A) {
;     ...
;         const u32x4 r0 = *(const u32x4*)(xb + (size_t)row * DM + c8); const int row2 = (row + (int)gridDim.x * 4 < NTOK) ? row + (int)gridDim.x * 4 : row; const u32x4 r1 = *(const u32x4*)(xb + (size_t)row2 * DM + c8);
;         float s0, s1;
;         { const f32x4 p0 = *(const f32x4*)(ss4 + (size_t)row * 16), p1 = *(const f32x4*)(ss4 + (size_t)row * 16 + 4), p2 = *(const f32x4*)(ss4 + (size_t)row * 16 + 8), p3 = *(const f32x4*)(ss4 + (size_t)row * 16 + 12);
;             s0 = ((((p0[0] + p0[1]) + (p0[2] + p0[3])) + ((p1[0] + p1[1]) + (p1[2] + p1[3]))) + (((p2[0] + p2[1]) + (p2[2] + p2[3])) + ((p3[0] + p3[1]) + (p3[2] + p3[3])))); }
;         { const f32x4 p0 = *(const f32x4*)(ss4 + (size_t)row2 * 16), p1 = *(const f32x4*)(ss4 + (size_t)row2 * 16 + 4), p2 = *(const f32x4*)(ss4 + (size_t)row2 * 16 + 8), p3 = *(const f32x4*)(ss4 + (size_t)row2 * 16 + 12);
;             s1 = ((((p0[0] + p0[1]) + (p0[2] + p0[3])) + ((p1[0] + p1[1]) + (p1[2] + p1[3]))) + (((p2[0] + p2[1]) + (p2[2] + p2[3])) + ((p3[0] + p3[1]) + (p3[2] + p3[3])))); }
;         float f[8]; unpack8(r0, f); float rs = rsqrtf(s0 * (1.0f / 1024.0f) + EPS);
;         *(f32x4*)(out + (size_t)row * DM + c8) = (f32x4){f[0], f[1], f[2], f[3]} * rs * g0; *(f32x4*)(out + (size_t)row * DM + c8 + 4) = (f32x4){f[4], f[5], f[6], f[7]} * rs * g1;
;         unpack8(r1, f); rs = rsqrtf(s1 * (1.0f / 1024.0f) + EPS);
;         *(f32x4*)(out + (size_t)row2 * DM + c8) = (f32x4){f[0], f[1], f[2], f[3]} * rs * g0; *(f32x4*)(out + (size_t)row2 * DM + c8 + 4) = (f32x4){f[4], f[5], f[6], f[7]} * rs * g1;
	v_lshlrev_b32_e32 v28, 16, v52
	v_mul_f32_e32 v14, 0x45800000, v24
	v_and_b32_e32 v29, 0xffff0000, v52
	v_lshlrev_b32_e32 v30, 16, v53
	v_and_b32_e32 v31, 0xffff0000, v53
	v_cndmask_b32_e64 v18, v24, v14, s[0:1]
	v_pk_mul_f32 v[14:15], v[18:19], v[28:29] op_sel_hi:[0,1]
	v_pk_mul_f32 v[16:17], v[18:19], v[30:31] op_sel_hi:[0,1]
	v_lshlrev_b64 v[20:21], 12, v[56:57]
	v_lshlrev_b32_e32 v36, 16, v54
	v_and_b32_e32 v37, 0xffff0000, v54
	v_lshlrev_b32_e32 v38, 16, v55
	v_and_b32_e32 v39, 0xffff0000, v55
	v_pk_mul_f32 v[16:17], v[6:7], v[16:17]
	v_pk_mul_f32 v[14:15], v[4:5], v[14:15]
	v_lshl_add_u64 v[20:21], v[10:11], 0, v[20:21]
	global_store_dwordx4 v[20:21], v[14:17], off
	s_nop 1
	v_pk_mul_f32 v[14:15], v[18:19], v[36:37] op_sel_hi:[0,1]
	v_pk_mul_f32 v[16:17], v[18:19], v[38:39] op_sel_hi:[0,1]
	v_pk_mul_f32 v[18:19], v[2:3], v[16:17]
	v_pk_mul_f32 v[16:17], v[0:1], v[14:15]
	global_store_dwordx4 v[20:21], v[16:19], off offset:16
	s_waitcnt vmcnt(13)
	v_mov_b32_e32 v78, v80
	s_waitcnt vmcnt(12)
	v_mov_b32_e32 v79, v84
	v_mov_b32_e32 v84, v81
	v_mov_b32_e32 v80, v82
	v_mov_b32_e32 v81, v86
	v_mov_b32_e32 v86, v83
	s_waitcnt vmcnt(11)
	v_mov_b32_e32 v82, v88
	s_waitcnt vmcnt(10)
	v_mov_b32_e32 v83, v92
	v_mov_b32_e32 v92, v89
	v_mov_b32_e32 v88, v90
	v_mov_b32_e32 v89, v94
	v_mov_b32_e32 v94, v91
	v_pk_add_f32 v[78:79], v[78:79], v[84:85]
	v_pk_add_f32 v[80:81], v[80:81], v[86:87]
	v_pk_add_f32 v[82:83], v[82:83], v[92:93]
	v_pk_add_f32 v[84:85], v[88:89], v[94:95]
	v_pk_add_f32 v[78:79], v[78:79], v[80:81]
	v_pk_add_f32 v[80:81], v[82:83], v[84:85]
	s_waitcnt vmcnt(8)
	v_mov_b32_e32 v82, v100
	s_waitcnt vmcnt(7)
	v_mov_b32_e32 v83, v104
	v_mov_b32_e32 v104, v101
	v_mov_b32_e32 v84, v102
	v_mov_b32_e32 v85, v106
	v_mov_b32_e32 v106, v103
	s_waitcnt vmcnt(6)
	v_mov_b32_e32 v86, v108
	s_waitcnt vmcnt(5)
	v_mov_b32_e32 v87, v112
	v_mov_b32_e32 v112, v109
	v_mov_b32_e32 v88, v110
	v_mov_b32_e32 v89, v114
	v_mov_b32_e32 v114, v111
	v_pk_add_f32 v[78:79], v[78:79], v[80:81]
	v_pk_add_f32 v[80:81], v[82:83], v[104:105]
	v_pk_add_f32 v[82:83], v[84:85], v[106:107]
	v_pk_add_f32 v[84:85], v[86:87], v[112:113]
	v_pk_add_f32 v[86:87], v[88:89], v[114:115]
	v_pk_add_f32 v[80:81], v[80:81], v[82:83]
	v_pk_add_f32 v[82:83], v[84:85], v[86:87]
	v_mov_b32_e32 v85, v78
	v_pk_add_f32 v[80:81], v[80:81], v[82:83]
	v_lshlrev_b32_e32 v90, 16, v96
	v_mov_b32_e32 v84, v80
	v_mov_b32_e32 v78, v81
	v_pk_add_f32 v[78:79], v[84:85], v[78:79]
	v_and_b32_e32 v91, 0xffff0000, v96
	v_pk_fma_f32 v[78:79], v[78:79], s[6:7], v[12:13] op_sel_hi:[1,0,0]
	v_lshlrev_b32_e32 v96, 16, v97
	v_mul_f32_e32 v80, 0x4b800000, v79
	v_cmp_gt_f32_e32 vcc, s9, v79
	v_mul_f32_e32 v81, 0x4b800000, v78
	v_cmp_gt_f32_e64 s[0:1], s9, v78
	v_cndmask_b32_e32 v79, v79, v80, vcc
	v_rsq_f32_e32 v79, v79
	v_cndmask_b32_e64 v78, v78, v81, s[0:1]
	v_rsq_f32_e32 v88, v78
	v_and_b32_e32 v97, 0xffff0000, v97
	v_mul_f32_e32 v78, 0x45800000, v79
	v_cndmask_b32_e32 v78, v79, v78, vcc
	v_lshlrev_b32_e32 v124, 16, v98
	v_and_b32_e32 v125, 0xffff0000, v98
	v_lshlrev_b32_e32 v98, 16, v99
	v_and_b32_e32 v99, 0xffff0000, v99
	v_pk_mul_f32 v[82:83], v[78:79], v[90:91] op_sel_hi:[0,1]
	v_pk_mul_f32 v[80:81], v[78:79], v[96:97] op_sel_hi:[0,1]
	v_pk_mul_f32 v[86:87], v[78:79], v[124:125] op_sel_hi:[0,1]
	v_pk_mul_f32 v[84:85], v[78:79], v[98:99] op_sel_hi:[0,1]
	v_pk_mul_f32 v[80:81], v[6:7], v[80:81]
	v_pk_mul_f32 v[78:79], v[4:5], v[82:83]
	v_pk_mul_f32 v[84:85], v[2:3], v[84:85]
	v_pk_mul_f32 v[82:83], v[0:1], v[86:87]
	global_store_dwordx4 v[122:123], v[78:81], off
	global_store_dwordx4 v[122:123], v[82:85], off offset:16
	s_waitcnt vmcnt(6)
	v_lshlrev_b32_e32 v92, 16, v116
	v_mul_f32_e32 v78, 0x45800000, v88
	v_and_b32_e32 v93, 0xffff0000, v116
	v_lshlrev_b32_e32 v94, 16, v117
	v_and_b32_e32 v95, 0xffff0000, v117
	v_cndmask_b32_e64 v82, v88, v78, s[0:1]
	v_pk_mul_f32 v[78:79], v[82:83], v[92:93] op_sel_hi:[0,1]
	v_pk_mul_f32 v[80:81], v[82:83], v[94:95] op_sel_hi:[0,1]
	v_lshlrev_b64 v[84:85], 12, v[120:121]
	v_lshlrev_b32_e32 v100, 16, v118
	v_and_b32_e32 v101, 0xffff0000, v118
	v_lshlrev_b32_e32 v102, 16, v119
	v_and_b32_e32 v103, 0xffff0000, v119
	v_pk_mul_f32 v[80:81], v[6:7], v[80:81]
	v_pk_mul_f32 v[78:79], v[4:5], v[78:79]
	v_lshl_add_u64 v[84:85], v[10:11], 0, v[84:85]
	global_store_dwordx4 v[84:85], v[78:81], off
	s_nop 1
	v_pk_mul_f32 v[78:79], v[82:83], v[100:101] op_sel_hi:[0,1]
	v_pk_mul_f32 v[80:81], v[82:83], v[102:103] op_sel_hi:[0,1]
	v_pk_mul_f32 v[82:83], v[2:3], v[80:81]
	v_pk_mul_f32 v[80:81], v[0:1], v[78:79]
	global_store_dwordx4 v[84:85], v[80:83], off offset:16
	v_add_u32_e32 v14, s8, v77
	v_cmp_lt_i32_e32 vcc, s10, v14
	s_or_b64 s[4:5], vcc, s[4:5]
	s_andn2_b64 exec, exec, s[4:5]
	s_cbranch_execnz .LBB0_1351
